# v57 + mirrored boustrophedon for the two segments with hipcc's shifted accumulator chain (in-proj M3, out-proj M3) instead of the plain pair order
# speedup vs baseline: 1.0161x; 1.0052x over previous
; #define PG8_STAGE(bufoff, gbase, voff) do { _Pragma("unroll") for (int _i = 0; _i < 2; ++_i) \
;         __builtin_amdgcn_global_load_lds((const unsigned*)((const char*)(gbase) + (voff)[_i]), (PG8_LAS unsigned*)(lds + (bufoff) + ldsw + _i * 8192), 16, 0, 0); } while (0)
; #define PG8_LDA(dst, b, h) do { _Pragma("unroll") for (int m = 0; m < 4; ++m) _Pragma("unroll") for (int k = 0; k < 2; ++k) dst[m][k] = *(const PG8_LAS bf16x8*)(lds + PG8_SA(b, h) + aoff + m * 2048 + k * 1024); } while (0)
; #define PG8_LDB(dst, b, h) do { _Pragma("unroll") for (int n = 0; n < 2; ++n) _Pragma("unroll") for (int k = 0; k < 2; ++k) dst[n][k] = *(const PG8_LAS bf16x8*)(lds + PG8_SB(b, h) + boff + n * 2048 + k * 1024); } while (0)
; #define PG8_MMA(ai, bj, At, Bt) do { __builtin_amdgcn_s_setprio(1); _Pragma("unroll") for (int m = 0; m < 4; ++m) _Pragma("unroll") for (int n = 0; n < 2; ++n) _Pragma("unroll") for (int k = 0; k < 2; ++k) \
;         acc[ai][bj][m][n] = __builtin_amdgcn_mfma_f32_16x16x32_bf16(Bt[n][k], At[m][k], acc[ai][bj][m][n], 0, 0, 0); __builtin_amdgcn_s_setprio(0); } while (0)
; #define PG8_WAIT_V(n) asm volatile("s_waitcnt vmcnt(" #n ")" ::: "memory")
; #define PG8_WAIT_L(n) asm volatile("s_waitcnt lgkmcnt(" #n ")" ::: "memory")
; #define PG8_BAR __builtin_amdgcn_s_barrier()
; #define PG8_SCHED __builtin_amdgcn_sched_barrier(0)
; template <class Epi, class Sched, bool ALIGN_EPI = false, bool SP2 = false>
; __device__ __forceinline__ void gemm_phase(PG8_LAS unsigned char* lds, const Gemm g, const Sched& S, const Epi& E) {
;     ...
;             PG8_LDB(B0, 0, 0); PG8_LDB(B1, 0, 1); PG8_SCHED; PG8_LDA(At, 0, 0); PG8_STAGE(PG8_SA(1, 1), a1 + hstep, voffA);
;             PG8_WAIT_V(8); PG8_WAIT_L(0); PG8_BAR; PG8_MMA(0, 0, At, B0); PG8_MMA(0, 1, At, B1); PG8_BAR; PG8_SCHED;
;             PG8_LDA(At, 0, 1); PG8_STAGE(PG8_SB(0, 0), b2, voffB); PG8_STAGE(PG8_SB(0, 1), b2 + hstep, voffB); PG8_STAGE(PG8_SA(0, 0), a2, voffA);
;             PG8_WAIT_V(8); PG8_WAIT_L(0); PG8_BAR; PG8_MMA(1, 0, At, B0); PG8_MMA(1, 1, At, B1); PG8_BAR; PG8_SCHED;
.LBB0_349:
	ds_read_b128 v[150:153], v169
	ds_read_b128 v[154:157], v169 offset:1024
	ds_read_b128 v[158:161], v169 offset:2048
	ds_read_b128 v[162:165], v169 offset:3072
	ds_read_b128 v[174:177], v170
	ds_read_b128 v[178:181], v170 offset:1024
	ds_read_b128 v[182:185], v170 offset:2048
	ds_read_b128 v[186:189], v170 offset:3072
	s_add_u32 s0, s88, 0xfff00080
	s_addc_u32 s1, s89, -1
	s_cmp_eq_u32 s23, 60
	s_cselect_b32 s93, s51, s1
	s_cselect_b32 s92, s50, s0
	s_cselect_b32 s91, s53, s21
	s_cselect_b32 s90, s52, s9
	ds_read_b128 v[190:193], v171
	ds_read_b128 v[196:199], v171 offset:1024
	ds_read_b128 v[200:203], v171 offset:2048
	ds_read_b128 v[204:207], v171 offset:3072
	ds_read_b128 v[208:211], v171 offset:4096
	ds_read_b128 v[212:215], v171 offset:5120
	ds_read_b128 v[220:223], v171 offset:6144
	ds_read_b128 v[224:227], v171 offset:7168
	s_add_u32 s0, s88, 0xfff00000
	s_addc_u32 s1, s89, -1
	s_add_i32 m0, s27, 0x8000
	s_nop 0
	global_load_lds_dwordx4 v134, s[0:1]
	s_add_i32 m0, s27, 0xa000
	s_nop 0
	global_load_lds_dwordx4 v138, s[0:1]
	s_add_i32 m0, s27, 0xc000
	s_nop 0
	global_load_lds_dwordx4 v134, s[88:89]
	s_add_i32 m0, s27, 0xe000
	s_nop 0
	global_load_lds_dwordx4 v138, s[88:89]
	s_waitcnt lgkmcnt(0)
	s_setprio 1
	v_mfma_f32_16x16x32_bf16 v[38:41], v[150:153], v[190:193], v[38:41]
	v_mfma_f32_16x16x32_bf16 v[38:41], v[154:157], v[196:199], v[38:41]
	v_mfma_f32_16x16x32_bf16 v[30:33], v[158:161], v[190:193], v[30:33]
	v_mfma_f32_16x16x32_bf16 v[30:33], v[162:165], v[196:199], v[30:33]
	v_mfma_f32_16x16x32_bf16 v[50:53], v[174:177], v[190:193], v[50:53]
	v_mfma_f32_16x16x32_bf16 v[50:53], v[178:181], v[196:199], v[50:53]
	v_mfma_f32_16x16x32_bf16 v[46:49], v[182:185], v[190:193], v[46:49]
	v_mfma_f32_16x16x32_bf16 v[46:49], v[186:189], v[196:199], v[46:49]
	v_mfma_f32_16x16x32_bf16 v[118:121], v[182:185], v[200:203], v[118:121]
	v_mfma_f32_16x16x32_bf16 v[118:121], v[186:189], v[204:207], v[118:121]
	v_mfma_f32_16x16x32_bf16 v[122:125], v[174:177], v[200:203], v[122:125]
	v_mfma_f32_16x16x32_bf16 v[122:125], v[178:181], v[204:207], v[122:125]
	v_mfma_f32_16x16x32_bf16 v[126:129], v[158:161], v[200:203], v[126:129]
	v_mfma_f32_16x16x32_bf16 v[126:129], v[162:165], v[204:207], v[126:129]
	v_mfma_f32_16x16x32_bf16 v[130:133], v[150:153], v[200:203], v[130:133]
	v_mfma_f32_16x16x32_bf16 v[130:133], v[154:157], v[204:207], v[130:133]
	v_mfma_f32_16x16x32_bf16 v[114:117], v[150:153], v[208:211], v[114:117]
	v_mfma_f32_16x16x32_bf16 v[114:117], v[154:157], v[212:215], v[114:117]
	v_mfma_f32_16x16x32_bf16 v[110:113], v[158:161], v[208:211], v[110:113]
	v_mfma_f32_16x16x32_bf16 v[110:113], v[162:165], v[212:215], v[110:113]
	v_mfma_f32_16x16x32_bf16 v[106:109], v[174:177], v[208:211], v[106:109]
	v_mfma_f32_16x16x32_bf16 v[106:109], v[178:181], v[212:215], v[106:109]
	v_mfma_f32_16x16x32_bf16 v[102:105], v[182:185], v[208:211], v[102:105]
	v_mfma_f32_16x16x32_bf16 v[102:105], v[186:189], v[212:215], v[102:105]
	v_mfma_f32_16x16x32_bf16 v[86:89], v[182:185], v[220:223], v[86:89]
	v_mfma_f32_16x16x32_bf16 v[86:89], v[186:189], v[224:227], v[86:89]
	v_mfma_f32_16x16x32_bf16 v[90:93], v[174:177], v[220:223], v[90:93]
	v_mfma_f32_16x16x32_bf16 v[90:93], v[178:181], v[224:227], v[90:93]
	v_mfma_f32_16x16x32_bf16 v[94:97], v[158:161], v[220:223], v[94:97]
	v_mfma_f32_16x16x32_bf16 v[94:97], v[162:165], v[224:227], v[94:97]
	v_mfma_f32_16x16x32_bf16 v[98:101], v[150:153], v[220:223], v[98:101]
	v_mfma_f32_16x16x32_bf16 v[98:101], v[154:157], v[224:227], v[98:101]
	s_setprio 0
	s_waitcnt vmcnt(8)
	s_barrier
	ds_read_b128 v[190:193], v171 offset:16384
	ds_read_b128 v[196:199], v171 offset:17408
	ds_read_b128 v[200:203], v171 offset:18432
	ds_read_b128 v[204:207], v171 offset:19456
	ds_read_b128 v[208:211], v171 offset:20480
	ds_read_b128 v[212:215], v171 offset:21504
	ds_read_b128 v[220:223], v171 offset:22528
	ds_read_b128 v[224:227], v171 offset:23552
	s_add_u32 vcc_lo, s90, 0x100000
	s_addc_u32 vcc_hi, s91, 0
	s_add_i32 m0, s27, 0x10000
	s_nop 0
	global_load_lds_dwordx4 v136, s[90:91]
	s_add_i32 m0, s27, 0x12000
	s_nop 0
	global_load_lds_dwordx4 v140, s[90:91]
	s_add_i32 m0, s27, 0x14000
	s_nop 0
	global_load_lds_dwordx4 v136, vcc
	s_add_i32 m0, s27, 0x16000
	s_nop 0
	global_load_lds_dwordx4 v140, vcc
	s_waitcnt lgkmcnt(0)
	s_setprio 1
	v_mfma_f32_16x16x32_bf16 v[82:85], v[150:153], v[190:193], v[82:85]
	v_mfma_f32_16x16x32_bf16 v[82:85], v[154:157], v[196:199], v[82:85]
	v_mfma_f32_16x16x32_bf16 v[78:81], v[158:161], v[190:193], v[78:81]
	v_mfma_f32_16x16x32_bf16 v[78:81], v[162:165], v[196:199], v[78:81]
	v_mfma_f32_16x16x32_bf16 v[74:77], v[174:177], v[190:193], v[74:77]
	v_mfma_f32_16x16x32_bf16 v[74:77], v[178:181], v[196:199], v[74:77]
	v_mfma_f32_16x16x32_bf16 v[70:73], v[182:185], v[190:193], v[70:73]
	v_mfma_f32_16x16x32_bf16 v[70:73], v[186:189], v[196:199], v[70:73]
	v_mfma_f32_16x16x32_bf16 v[54:57], v[182:185], v[200:203], v[54:57]
	v_mfma_f32_16x16x32_bf16 v[54:57], v[186:189], v[204:207], v[54:57]
	v_mfma_f32_16x16x32_bf16 v[58:61], v[174:177], v[200:203], v[58:61]
	v_mfma_f32_16x16x32_bf16 v[58:61], v[178:181], v[204:207], v[58:61]
	v_mfma_f32_16x16x32_bf16 v[62:65], v[158:161], v[200:203], v[62:65]
	v_mfma_f32_16x16x32_bf16 v[62:65], v[162:165], v[204:207], v[62:65]
	v_mfma_f32_16x16x32_bf16 v[66:69], v[150:153], v[200:203], v[66:69]
	v_mfma_f32_16x16x32_bf16 v[66:69], v[154:157], v[204:207], v[66:69]
	v_mfma_f32_16x16x32_bf16 v[42:45], v[150:153], v[208:211], v[42:45]
	v_mfma_f32_16x16x32_bf16 v[42:45], v[154:157], v[212:215], v[42:45]
	v_mfma_f32_16x16x32_bf16 v[34:37], v[158:161], v[208:211], v[34:37]
	v_mfma_f32_16x16x32_bf16 v[34:37], v[162:165], v[212:215], v[34:37]
	v_mfma_f32_16x16x32_bf16 v[26:29], v[174:177], v[208:211], v[26:29]
	v_mfma_f32_16x16x32_bf16 v[26:29], v[178:181], v[212:215], v[26:29]
	v_mfma_f32_16x16x32_bf16 v[22:25], v[182:185], v[208:211], v[22:25]
	v_mfma_f32_16x16x32_bf16 v[22:25], v[186:189], v[212:215], v[22:25]
	v_mfma_f32_16x16x32_bf16 v[4:7], v[182:185], v[220:223], v[6:9]
	v_mfma_f32_16x16x32_bf16 v[4:7], v[186:189], v[224:227], v[4:7]
	v_mfma_f32_16x16x32_bf16 v[10:13], v[174:177], v[220:223], v[10:13]
	v_mfma_f32_16x16x32_bf16 v[10:13], v[178:181], v[224:227], v[10:13]
	v_mfma_f32_16x16x32_bf16 v[14:17], v[158:161], v[220:223], v[14:17]
	v_mfma_f32_16x16x32_bf16 v[14:17], v[162:165], v[224:227], v[14:17]
	v_mfma_f32_16x16x32_bf16 v[18:21], v[150:153], v[220:223], v[18:21]
	v_mfma_f32_16x16x32_bf16 v[18:21], v[154:157], v[224:227], v[18:21]
	s_setprio 0
	s_waitcnt vmcnt(6)
	s_barrier
; #define PG8_STAGE(bufoff, gbase, voff) do { _Pragma("unroll") for (int _i = 0; _i < 2; ++_i) \
;         __builtin_amdgcn_global_load_lds((const unsigned*)((const char*)(gbase) + (voff)[_i]), (PG8_LAS unsigned*)(lds + (bufoff) + ldsw + _i * 8192), 16, 0, 0); } while (0)
; #define PG8_LDA(dst, b, h) do { _Pragma("unroll") for (int m = 0; m < 4; ++m) _Pragma("unroll") for (int k = 0; k < 2; ++k) dst[m][k] = *(const PG8_LAS bf16x8*)(lds + PG8_SA(b, h) + aoff + m * 2048 + k * 1024); } while (0)
; #define PG8_LDB(dst, b, h) do { _Pragma("unroll") for (int n = 0; n < 2; ++n) _Pragma("unroll") for (int k = 0; k < 2; ++k) dst[n][k] = *(const PG8_LAS bf16x8*)(lds + PG8_SB(b, h) + boff + n * 2048 + k * 1024); } while (0)
; #define PG8_MMA(ai, bj, At, Bt) do { __builtin_amdgcn_s_setprio(1); _Pragma("unroll") for (int m = 0; m < 4; ++m) _Pragma("unroll") for (int n = 0; n < 2; ++n) _Pragma("unroll") for (int k = 0; k < 2; ++k) \
;         acc[ai][bj][m][n] = __builtin_amdgcn_mfma_f32_16x16x32_bf16(Bt[n][k], At[m][k], acc[ai][bj][m][n], 0, 0, 0); __builtin_amdgcn_s_setprio(0); } while (0)
; #define PG8_WAIT_V(n) asm volatile("s_waitcnt vmcnt(" #n ")" ::: "memory")
; #define PG8_WAIT_L(n) asm volatile("s_waitcnt lgkmcnt(" #n ")" ::: "memory")
; #define PG8_BAR __builtin_amdgcn_s_barrier()
; #define PG8_SCHED __builtin_amdgcn_sched_barrier(0)
; template <class Epi, class Sched, bool ALIGN_EPI = false, bool SP2 = false>
; __device__ __forceinline__ void gemm_phase(PG8_LAS unsigned char* lds, const Gemm g, const Sched& S, const Epi& E) {
;     ...
;             PG8_LDB(B0, 1, 0); PG8_LDB(B1, 1, 1); PG8_SCHED; PG8_LDA(At, 1, 0); PG8_STAGE(PG8_SA(0, 1), a2 + hstep, voffA);
;             PG8_WAIT_V(8); PG8_WAIT_L(0); PG8_BAR; PG8_MMA(0, 0, At, B0); PG8_MMA(0, 1, At, B1); PG8_BAR; PG8_SCHED;
;             PG8_LDA(At, 1, 1); PG8_STAGE(PG8_SB(1, 0), b3, voffB); PG8_STAGE(PG8_SB(1, 1), b3 + hstep, voffB); PG8_STAGE(PG8_SA(1, 0), a3, voffA);
;             PG8_WAIT_V(8); PG8_WAIT_L(0); PG8_BAR; PG8_MMA(1, 0, At, B0); PG8_MMA(1, 1, At, B1); PG8_BAR; PG8_SCHED;
	s_add_i32 s0, 0, 0x18000
	v_add_u32_e32 v3, s0, v167
	s_add_i32 s1, 0, 0x1c000
	ds_read_b128 v[150:153], v3
	ds_read_b128 v[154:157], v3 offset:1024
	ds_read_b128 v[158:161], v3 offset:2048
	ds_read_b128 v[162:165], v3 offset:3072
	v_add_u32_e32 v3, s1, v167
	ds_read_b128 v[174:177], v3
	ds_read_b128 v[178:181], v3 offset:1024
	ds_read_b128 v[182:185], v3 offset:2048
	ds_read_b128 v[186:189], v3 offset:3072
	ds_read_b128 v[190:193], v171 offset:32768
	ds_read_b128 v[196:199], v171 offset:33792
	ds_read_b128 v[200:203], v171 offset:34816
	ds_read_b128 v[204:207], v171 offset:35840
	ds_read_b128 v[208:211], v171 offset:36864
	ds_read_b128 v[212:215], v171 offset:37888
	ds_read_b128 v[220:223], v171 offset:38912
	ds_read_b128 v[224:227], v171 offset:39936
	s_add_u32 vcc_lo, s92, 0x100000
	s_addc_u32 vcc_hi, s93, 0
	s_mov_b32 m0, s27
	s_nop 0
	global_load_lds_dwordx4 v134, s[92:93]
	s_add_i32 m0, s27, 0x2000
	s_nop 0
	global_load_lds_dwordx4 v138, s[92:93]
	s_add_i32 m0, s27, 0x4000
	s_nop 0
	global_load_lds_dwordx4 v134, vcc
	s_add_i32 m0, s27, 0x6000
	s_nop 0
	global_load_lds_dwordx4 v138, vcc
	s_waitcnt lgkmcnt(0)
	s_setprio 1
	v_mfma_f32_16x16x32_bf16 v[38:41], v[150:153], v[190:193], v[38:41]
	v_mfma_f32_16x16x32_bf16 v[38:41], v[154:157], v[196:199], v[38:41]
	v_mfma_f32_16x16x32_bf16 v[30:33], v[158:161], v[190:193], v[30:33]
	v_mfma_f32_16x16x32_bf16 v[30:33], v[162:165], v[196:199], v[30:33]
	v_mfma_f32_16x16x32_bf16 v[50:53], v[174:177], v[190:193], v[50:53]
	v_mfma_f32_16x16x32_bf16 v[50:53], v[178:181], v[196:199], v[50:53]
	v_mfma_f32_16x16x32_bf16 v[46:49], v[182:185], v[190:193], v[46:49]
	v_mfma_f32_16x16x32_bf16 v[46:49], v[186:189], v[196:199], v[46:49]
	v_mfma_f32_16x16x32_bf16 v[118:121], v[182:185], v[200:203], v[118:121]
	v_mfma_f32_16x16x32_bf16 v[118:121], v[186:189], v[204:207], v[118:121]
	v_mfma_f32_16x16x32_bf16 v[122:125], v[174:177], v[200:203], v[122:125]
	v_mfma_f32_16x16x32_bf16 v[122:125], v[178:181], v[204:207], v[122:125]
	v_mfma_f32_16x16x32_bf16 v[126:129], v[158:161], v[200:203], v[126:129]
	v_mfma_f32_16x16x32_bf16 v[126:129], v[162:165], v[204:207], v[126:129]
	v_mfma_f32_16x16x32_bf16 v[130:133], v[150:153], v[200:203], v[130:133]
	v_mfma_f32_16x16x32_bf16 v[130:133], v[154:157], v[204:207], v[130:133]
	v_mfma_f32_16x16x32_bf16 v[114:117], v[150:153], v[208:211], v[114:117]
	v_mfma_f32_16x16x32_bf16 v[114:117], v[154:157], v[212:215], v[114:117]
	v_mfma_f32_16x16x32_bf16 v[110:113], v[158:161], v[208:211], v[110:113]
	v_mfma_f32_16x16x32_bf16 v[110:113], v[162:165], v[212:215], v[110:113]
	v_mfma_f32_16x16x32_bf16 v[106:109], v[174:177], v[208:211], v[106:109]
	v_mfma_f32_16x16x32_bf16 v[106:109], v[178:181], v[212:215], v[106:109]
	v_mfma_f32_16x16x32_bf16 v[102:105], v[182:185], v[208:211], v[102:105]
	v_mfma_f32_16x16x32_bf16 v[102:105], v[186:189], v[212:215], v[102:105]
	v_mfma_f32_16x16x32_bf16 v[86:89], v[182:185], v[220:223], v[86:89]
	v_mfma_f32_16x16x32_bf16 v[86:89], v[186:189], v[224:227], v[86:89]
	v_mfma_f32_16x16x32_bf16 v[90:93], v[174:177], v[220:223], v[90:93]
	v_mfma_f32_16x16x32_bf16 v[90:93], v[178:181], v[224:227], v[90:93]
	v_mfma_f32_16x16x32_bf16 v[94:97], v[158:161], v[220:223], v[94:97]
	v_mfma_f32_16x16x32_bf16 v[94:97], v[162:165], v[224:227], v[94:97]
	v_mfma_f32_16x16x32_bf16 v[98:101], v[150:153], v[220:223], v[98:101]
	v_mfma_f32_16x16x32_bf16 v[98:101], v[154:157], v[224:227], v[98:101]
	s_setprio 0
	s_waitcnt vmcnt(8)
	s_barrier
	ds_read_b128 v[190:193], v171 offset:49152
	ds_read_b128 v[196:199], v171 offset:50176
	ds_read_b128 v[200:203], v171 offset:51200
	ds_read_b128 v[204:207], v171 offset:52224
	ds_read_b128 v[208:211], v171 offset:53248
	ds_read_b128 v[212:215], v171 offset:54272
	ds_read_b128 v[220:223], v171 offset:55296
	ds_read_b128 v[224:227], v171 offset:56320
	s_add_u32 s0, s90, 0x80
	s_addc_u32 s1, s91, 0
	s_add_u32 vcc_lo, s0, 0x100000
	s_addc_u32 vcc_hi, s1, 0
	s_add_i32 m0, s27, 0x18000
	s_nop 0
	global_load_lds_dwordx4 v136, s[0:1]
	s_add_i32 m0, s27, 0x1a000
	s_nop 0
	global_load_lds_dwordx4 v140, s[0:1]
	s_add_i32 m0, s27, 0x1c000
	s_nop 0
	global_load_lds_dwordx4 v136, vcc
	s_add_i32 m0, s27, 0x1e000
	s_nop 0
	global_load_lds_dwordx4 v140, vcc
	s_waitcnt lgkmcnt(0)
	s_setprio 1
	v_mfma_f32_16x16x32_bf16 v[70:73], v[182:185], v[190:193], v[70:73]
	v_mfma_f32_16x16x32_bf16 v[70:73], v[186:189], v[196:199], v[70:73]
	v_mfma_f32_16x16x32_bf16 v[74:77], v[174:177], v[190:193], v[74:77]
	v_mfma_f32_16x16x32_bf16 v[74:77], v[178:181], v[196:199], v[74:77]
	v_mfma_f32_16x16x32_bf16 v[78:81], v[158:161], v[190:193], v[78:81]
	v_mfma_f32_16x16x32_bf16 v[78:81], v[162:165], v[196:199], v[78:81]
	v_mfma_f32_16x16x32_bf16 v[82:85], v[150:153], v[190:193], v[82:85]
	v_mfma_f32_16x16x32_bf16 v[82:85], v[154:157], v[196:199], v[82:85]
	v_mfma_f32_16x16x32_bf16 v[66:69], v[150:153], v[200:203], v[66:69]
	v_mfma_f32_16x16x32_bf16 v[66:69], v[154:157], v[204:207], v[66:69]
	v_mfma_f32_16x16x32_bf16 v[62:65], v[158:161], v[200:203], v[62:65]
	v_mfma_f32_16x16x32_bf16 v[62:65], v[162:165], v[204:207], v[62:65]
	v_mfma_f32_16x16x32_bf16 v[58:61], v[174:177], v[200:203], v[58:61]
	v_mfma_f32_16x16x32_bf16 v[58:61], v[178:181], v[204:207], v[58:61]
	v_mfma_f32_16x16x32_bf16 v[54:57], v[182:185], v[200:203], v[54:57]
	v_mfma_f32_16x16x32_bf16 v[54:57], v[186:189], v[204:207], v[54:57]
	v_mfma_f32_16x16x32_bf16 v[22:25], v[182:185], v[208:211], v[22:25]
	v_mfma_f32_16x16x32_bf16 v[22:25], v[186:189], v[212:215], v[22:25]
	v_mfma_f32_16x16x32_bf16 v[26:29], v[174:177], v[208:211], v[26:29]
	v_mfma_f32_16x16x32_bf16 v[26:29], v[178:181], v[212:215], v[26:29]
	v_mfma_f32_16x16x32_bf16 v[34:37], v[158:161], v[208:211], v[34:37]
	v_mfma_f32_16x16x32_bf16 v[34:37], v[162:165], v[212:215], v[34:37]
	v_mfma_f32_16x16x32_bf16 v[42:45], v[150:153], v[208:211], v[42:45]
	v_mfma_f32_16x16x32_bf16 v[42:45], v[154:157], v[212:215], v[42:45]
	v_mfma_f32_16x16x32_bf16 v[18:21], v[150:153], v[220:223], v[18:21]
	v_mfma_f32_16x16x32_bf16 v[18:21], v[154:157], v[224:227], v[18:21]
	v_mfma_f32_16x16x32_bf16 v[14:17], v[158:161], v[220:223], v[14:17]
	v_mfma_f32_16x16x32_bf16 v[14:17], v[162:165], v[224:227], v[14:17]
	v_mfma_f32_16x16x32_bf16 v[8:11], v[174:177], v[220:223], v[10:13]
	v_mfma_f32_16x16x32_bf16 v[10:13], v[178:181], v[224:227], v[8:11]
	v_mfma_f32_16x16x32_bf16 v[4:7], v[182:185], v[220:223], v[4:7]
	v_mfma_f32_16x16x32_bf16 v[6:9], v[186:189], v[224:227], v[4:7]
	s_setprio 0
	s_waitcnt vmcnt(6)
	s_barrier
	s_add_i32 s23, s23, 2
	s_add_u32 s88, s88, 0x100
	s_addc_u32 s89, s89, 0
	s_add_u32 s9, s9, 0x100
	s_addc_u32 s21, s21, 0
	s_cmp_gt_u32 s23, 61
	s_cbranch_scc0 .LBB0_349
	s_branch .Lip_exit
; #define PG8_STAGE(bufoff, gbase, voff) do { _Pragma("unroll") for (int _i = 0; _i < 2; ++_i) \
;         __builtin_amdgcn_global_load_lds((const unsigned*)((const char*)(gbase) + (voff)[_i]), (PG8_LAS unsigned*)(lds + (bufoff) + ldsw + _i * 8192), 16, 0, 0); } while (0)
; #define PG8_LDA(dst, b, h) do { _Pragma("unroll") for (int m = 0; m < 4; ++m) _Pragma("unroll") for (int k = 0; k < 2; ++k) dst[m][k] = *(const PG8_LAS bf16x8*)(lds + PG8_SA(b, h) + aoff + m * 2048 + k * 1024); } while (0)
; #define PG8_LDB(dst, b, h) do { _Pragma("unroll") for (int n = 0; n < 2; ++n) _Pragma("unroll") for (int k = 0; k < 2; ++k) dst[n][k] = *(const PG8_LAS bf16x8*)(lds + PG8_SB(b, h) + boff + n * 2048 + k * 1024); } while (0)
; #define PG8_MMA(ai, bj, At, Bt) do { __builtin_amdgcn_s_setprio(1); _Pragma("unroll") for (int m = 0; m < 4; ++m) _Pragma("unroll") for (int n = 0; n < 2; ++n) _Pragma("unroll") for (int k = 0; k < 2; ++k) \
;         acc[ai][bj][m][n] = __builtin_amdgcn_mfma_f32_16x16x32_bf16(Bt[n][k], At[m][k], acc[ai][bj][m][n], 0, 0, 0); __builtin_amdgcn_s_setprio(0); } while (0)
; #define PG8_BAR __builtin_amdgcn_s_barrier()
; template <class Epi, class Sched, bool ALIGN_EPI = false, bool SP2 = false>
; __device__ __forceinline__ void gemm_phase(PG8_LAS unsigned char* lds, const Gemm g, const Sched& S, const Epi& E) {
;     ...
;             const bool last = (t == nt - 2);
;             const char* a1 = cA + (size_t)(t + 1) * kstep;
;             const char* a2 = last ? nA : cA + (size_t)(t + 2) * kstep; const char* b2 = last ? nB : cB + (size_t)(t + 2) * kstep;
;             const char* a3 = a2 + kstep; const char* b3 = b2 + kstep;
;             if (last && has_next) S.a_ready(nxt);
;             if constexpr (Epi::MIDK) { if (t == (nt >> 1)) { E.midk(acc, wr, fr); asm volatile("s_waitcnt lgkmcnt(0)" ::: "memory"); } }
;             if constexpr (SP2) {
;             PG8_LDB(B0, 0, 0); PG8_LDB(B1, 0, 1); PG8_SCHED; PG8_LDA(At, 0, 0); PG8_STAGE(PG8_SA(1, 1), a1 + hstep, voffA);
;             PG8_WAIT_V(8); PG8_WAIT_L(0); PG8_BAR; PG8_MMA(0, 0, At, B0); PG8_MMA(0, 1, At, B1); PG8_BAR; PG8_SCHED;
;             PG8_LDA(At, 0, 1); PG8_STAGE(PG8_SB(0, 0), b2, voffB); PG8_STAGE(PG8_SB(0, 1), b2 + hstep, voffB); PG8_STAGE(PG8_SA(0, 0), a2, voffA);
;             PG8_WAIT_V(8); PG8_WAIT_L(0); PG8_BAR; PG8_MMA(1, 0, At, B0); PG8_MMA(1, 1, At, B1); PG8_BAR; PG8_SCHED;
.Lip_h1:
	ds_read_b128 v[150:153], v169
	ds_read_b128 v[154:157], v169 offset:1024
	ds_read_b128 v[158:161], v169 offset:2048
	ds_read_b128 v[162:165], v169 offset:3072
	ds_read_b128 v[174:177], v170
	ds_read_b128 v[178:181], v170 offset:1024
	ds_read_b128 v[182:185], v170 offset:2048
	ds_read_b128 v[186:189], v170 offset:3072
	s_add_u32 s0, s88, 0xfff00080
	s_addc_u32 s1, s89, -1
	s_cmp_eq_u32 s23, 60
	s_cselect_b32 s93, s51, s1
	s_cselect_b32 s92, s50, s0
	s_cselect_b32 s91, s53, s21
	s_cselect_b32 s90, s52, s9
	ds_read_b128 v[190:193], v171
	ds_read_b128 v[196:199], v171 offset:1024
	ds_read_b128 v[200:203], v171 offset:2048
	ds_read_b128 v[204:207], v171 offset:3072
	ds_read_b128 v[208:211], v171 offset:4096
	ds_read_b128 v[212:215], v171 offset:5120
	ds_read_b128 v[220:223], v171 offset:6144
	ds_read_b128 v[224:227], v171 offset:7168
	s_add_u32 s0, s88, 0xfff00000
	s_addc_u32 s1, s89, -1
	s_add_i32 m0, s27, 0x8000
	s_nop 0
	global_load_lds_dwordx4 v134, s[0:1]
	s_add_i32 m0, s27, 0xa000
	s_nop 0
	global_load_lds_dwordx4 v138, s[0:1]
	s_add_i32 m0, s27, 0xc000
	s_nop 0
	global_load_lds_dwordx4 v134, s[88:89]
	s_add_i32 m0, s27, 0xe000
	s_nop 0
	global_load_lds_dwordx4 v138, s[88:89]
	s_sleep 2
	s_waitcnt lgkmcnt(0)
	s_waitcnt vmcnt(8)
	s_barrier
	s_setprio 2
	v_mfma_f32_16x16x32_bf16 v[38:41], v[150:153], v[190:193], v[38:41]
	v_mfma_f32_16x16x32_bf16 v[38:41], v[154:157], v[196:199], v[38:41]
	v_mfma_f32_16x16x32_bf16 v[30:33], v[158:161], v[190:193], v[30:33]
	v_mfma_f32_16x16x32_bf16 v[30:33], v[162:165], v[196:199], v[30:33]
	v_mfma_f32_16x16x32_bf16 v[50:53], v[174:177], v[190:193], v[50:53]
	v_mfma_f32_16x16x32_bf16 v[50:53], v[178:181], v[196:199], v[50:53]
	v_mfma_f32_16x16x32_bf16 v[46:49], v[182:185], v[190:193], v[46:49]
	v_mfma_f32_16x16x32_bf16 v[46:49], v[186:189], v[196:199], v[46:49]
	v_mfma_f32_16x16x32_bf16 v[118:121], v[182:185], v[200:203], v[118:121]
	v_mfma_f32_16x16x32_bf16 v[118:121], v[186:189], v[204:207], v[118:121]
	v_mfma_f32_16x16x32_bf16 v[122:125], v[174:177], v[200:203], v[122:125]
	v_mfma_f32_16x16x32_bf16 v[122:125], v[178:181], v[204:207], v[122:125]
	v_mfma_f32_16x16x32_bf16 v[126:129], v[158:161], v[200:203], v[126:129]
	v_mfma_f32_16x16x32_bf16 v[126:129], v[162:165], v[204:207], v[126:129]
	v_mfma_f32_16x16x32_bf16 v[130:133], v[150:153], v[200:203], v[130:133]
	v_mfma_f32_16x16x32_bf16 v[130:133], v[154:157], v[204:207], v[130:133]
	v_mfma_f32_16x16x32_bf16 v[114:117], v[150:153], v[208:211], v[114:117]
	v_mfma_f32_16x16x32_bf16 v[114:117], v[154:157], v[212:215], v[114:117]
	v_mfma_f32_16x16x32_bf16 v[110:113], v[158:161], v[208:211], v[110:113]
	v_mfma_f32_16x16x32_bf16 v[110:113], v[162:165], v[212:215], v[110:113]
	v_mfma_f32_16x16x32_bf16 v[106:109], v[174:177], v[208:211], v[106:109]
	v_mfma_f32_16x16x32_bf16 v[106:109], v[178:181], v[212:215], v[106:109]
	v_mfma_f32_16x16x32_bf16 v[102:105], v[182:185], v[208:211], v[102:105]
	v_mfma_f32_16x16x32_bf16 v[102:105], v[186:189], v[212:215], v[102:105]
	v_mfma_f32_16x16x32_bf16 v[86:89], v[182:185], v[220:223], v[86:89]
	v_mfma_f32_16x16x32_bf16 v[86:89], v[186:189], v[224:227], v[86:89]
	v_mfma_f32_16x16x32_bf16 v[90:93], v[174:177], v[220:223], v[90:93]
	v_mfma_f32_16x16x32_bf16 v[90:93], v[178:181], v[224:227], v[90:93]
	v_mfma_f32_16x16x32_bf16 v[94:97], v[158:161], v[220:223], v[94:97]
	v_mfma_f32_16x16x32_bf16 v[94:97], v[162:165], v[224:227], v[94:97]
	v_mfma_f32_16x16x32_bf16 v[98:101], v[150:153], v[220:223], v[98:101]
	v_mfma_f32_16x16x32_bf16 v[98:101], v[154:157], v[224:227], v[98:101]
	s_setprio 0
	ds_read_b128 v[190:193], v171 offset:16384
	ds_read_b128 v[196:199], v171 offset:17408
	ds_read_b128 v[200:203], v171 offset:18432
	ds_read_b128 v[204:207], v171 offset:19456
	ds_read_b128 v[208:211], v171 offset:20480
	ds_read_b128 v[212:215], v171 offset:21504
	ds_read_b128 v[220:223], v171 offset:22528
	ds_read_b128 v[224:227], v171 offset:23552
	s_add_u32 vcc_lo, s90, 0x100000
	s_addc_u32 vcc_hi, s91, 0
	s_add_i32 m0, s27, 0x10000
	s_nop 0
	global_load_lds_dwordx4 v136, s[90:91]
	s_add_i32 m0, s27, 0x12000
	s_nop 0
	global_load_lds_dwordx4 v140, s[90:91]
	s_add_i32 m0, s27, 0x14000
	s_nop 0
	global_load_lds_dwordx4 v136, vcc
	s_add_i32 m0, s27, 0x16000
	s_nop 0
	global_load_lds_dwordx4 v140, vcc
	s_sleep 2
	s_waitcnt lgkmcnt(0)
	s_waitcnt vmcnt(6)
	s_barrier
; #define PG8_STAGE(bufoff, gbase, voff) do { _Pragma("unroll") for (int _i = 0; _i < 2; ++_i) \
;         __builtin_amdgcn_global_load_lds((const unsigned*)((const char*)(gbase) + (voff)[_i]), (PG8_LAS unsigned*)(lds + (bufoff) + ldsw + _i * 8192), 16, 0, 0); } while (0)
; #define PG8_LDA(dst, b, h) do { _Pragma("unroll") for (int m = 0; m < 4; ++m) _Pragma("unroll") for (int k = 0; k < 2; ++k) dst[m][k] = *(const PG8_LAS bf16x8*)(lds + PG8_SA(b, h) + aoff + m * 2048 + k * 1024); } while (0)
; #define PG8_LDB(dst, b, h) do { _Pragma("unroll") for (int n = 0; n < 2; ++n) _Pragma("unroll") for (int k = 0; k < 2; ++k) dst[n][k] = *(const PG8_LAS bf16x8*)(lds + PG8_SB(b, h) + boff + n * 2048 + k * 1024); } while (0)
; #define PG8_MMA(ai, bj, At, Bt) do { __builtin_amdgcn_s_setprio(1); _Pragma("unroll") for (int m = 0; m < 4; ++m) _Pragma("unroll") for (int n = 0; n < 2; ++n) _Pragma("unroll") for (int k = 0; k < 2; ++k) \
;         acc[ai][bj][m][n] = __builtin_amdgcn_mfma_f32_16x16x32_bf16(Bt[n][k], At[m][k], acc[ai][bj][m][n], 0, 0, 0); __builtin_amdgcn_s_setprio(0); } while (0)
; #define PG8_WAIT_V(n) asm volatile("s_waitcnt vmcnt(" #n ")" ::: "memory")
; #define PG8_WAIT_L(n) asm volatile("s_waitcnt lgkmcnt(" #n ")" ::: "memory")
; #define PG8_BAR __builtin_amdgcn_s_barrier()
; #define PG8_SCHED __builtin_amdgcn_sched_barrier(0)
; template <class Epi, class Sched, bool ALIGN_EPI = false, bool SP2 = false>
; __device__ __forceinline__ void gemm_phase(PG8_LAS unsigned char* lds, const Gemm g, const Sched& S, const Epi& E) {
;     ...
;             PG8_LDA(At, 0, 1); PG8_STAGE(PG8_SB(0, 0), b2, voffB); PG8_STAGE(PG8_SB(0, 1), b2 + hstep, voffB); PG8_STAGE(PG8_SA(0, 0), a2, voffA);
;             PG8_WAIT_V(8); PG8_WAIT_L(0); PG8_BAR; PG8_MMA(1, 0, At, B0); PG8_MMA(1, 1, At, B1); PG8_BAR; PG8_SCHED;
;             PG8_LDB(B0, 1, 0); PG8_LDB(B1, 1, 1); PG8_SCHED; PG8_LDA(At, 1, 0); PG8_STAGE(PG8_SA(0, 1), a2 + hstep, voffA);
;             PG8_WAIT_V(8); PG8_WAIT_L(0); PG8_BAR; PG8_MMA(0, 0, At, B0); PG8_MMA(0, 1, At, B1); PG8_BAR; PG8_SCHED;
	s_setprio 2
	v_mfma_f32_16x16x32_bf16 v[82:85], v[150:153], v[190:193], v[82:85]
	v_mfma_f32_16x16x32_bf16 v[82:85], v[154:157], v[196:199], v[82:85]
	v_mfma_f32_16x16x32_bf16 v[78:81], v[158:161], v[190:193], v[78:81]
	v_mfma_f32_16x16x32_bf16 v[78:81], v[162:165], v[196:199], v[78:81]
	v_mfma_f32_16x16x32_bf16 v[74:77], v[174:177], v[190:193], v[74:77]
	v_mfma_f32_16x16x32_bf16 v[74:77], v[178:181], v[196:199], v[74:77]
	v_mfma_f32_16x16x32_bf16 v[70:73], v[182:185], v[190:193], v[70:73]
	v_mfma_f32_16x16x32_bf16 v[70:73], v[186:189], v[196:199], v[70:73]
	v_mfma_f32_16x16x32_bf16 v[54:57], v[182:185], v[200:203], v[54:57]
	v_mfma_f32_16x16x32_bf16 v[54:57], v[186:189], v[204:207], v[54:57]
	v_mfma_f32_16x16x32_bf16 v[58:61], v[174:177], v[200:203], v[58:61]
	v_mfma_f32_16x16x32_bf16 v[58:61], v[178:181], v[204:207], v[58:61]
	v_mfma_f32_16x16x32_bf16 v[62:65], v[158:161], v[200:203], v[62:65]
	v_mfma_f32_16x16x32_bf16 v[62:65], v[162:165], v[204:207], v[62:65]
	v_mfma_f32_16x16x32_bf16 v[66:69], v[150:153], v[200:203], v[66:69]
	v_mfma_f32_16x16x32_bf16 v[66:69], v[154:157], v[204:207], v[66:69]
	v_mfma_f32_16x16x32_bf16 v[42:45], v[150:153], v[208:211], v[42:45]
	v_mfma_f32_16x16x32_bf16 v[42:45], v[154:157], v[212:215], v[42:45]
	v_mfma_f32_16x16x32_bf16 v[34:37], v[158:161], v[208:211], v[34:37]
	v_mfma_f32_16x16x32_bf16 v[34:37], v[162:165], v[212:215], v[34:37]
	v_mfma_f32_16x16x32_bf16 v[26:29], v[174:177], v[208:211], v[26:29]
	v_mfma_f32_16x16x32_bf16 v[26:29], v[178:181], v[212:215], v[26:29]
	v_mfma_f32_16x16x32_bf16 v[22:25], v[182:185], v[208:211], v[22:25]
	v_mfma_f32_16x16x32_bf16 v[22:25], v[186:189], v[212:215], v[22:25]
	v_mfma_f32_16x16x32_bf16 v[4:7], v[182:185], v[220:223], v[6:9]
	v_mfma_f32_16x16x32_bf16 v[4:7], v[186:189], v[224:227], v[4:7]
	v_mfma_f32_16x16x32_bf16 v[10:13], v[174:177], v[220:223], v[10:13]
	v_mfma_f32_16x16x32_bf16 v[10:13], v[178:181], v[224:227], v[10:13]
	v_mfma_f32_16x16x32_bf16 v[14:17], v[158:161], v[220:223], v[14:17]
	v_mfma_f32_16x16x32_bf16 v[14:17], v[162:165], v[224:227], v[14:17]
	v_mfma_f32_16x16x32_bf16 v[18:21], v[150:153], v[220:223], v[18:21]
	v_mfma_f32_16x16x32_bf16 v[18:21], v[154:157], v[224:227], v[18:21]
	s_setprio 0
	s_add_i32 s0, 0, 0x18000
	v_add_u32_e32 v3, s0, v167
	s_add_i32 s1, 0, 0x1c000
	ds_read_b128 v[150:153], v3
	ds_read_b128 v[154:157], v3 offset:1024
	ds_read_b128 v[158:161], v3 offset:2048
	ds_read_b128 v[162:165], v3 offset:3072
	v_add_u32_e32 v3, s1, v167
	ds_read_b128 v[174:177], v3
	ds_read_b128 v[178:181], v3 offset:1024
	ds_read_b128 v[182:185], v3 offset:2048
	ds_read_b128 v[186:189], v3 offset:3072
	ds_read_b128 v[190:193], v171 offset:32768
	ds_read_b128 v[196:199], v171 offset:33792
	ds_read_b128 v[200:203], v171 offset:34816
	ds_read_b128 v[204:207], v171 offset:35840
	ds_read_b128 v[208:211], v171 offset:36864
	ds_read_b128 v[212:215], v171 offset:37888
	ds_read_b128 v[220:223], v171 offset:38912
	ds_read_b128 v[224:227], v171 offset:39936
	s_add_u32 vcc_lo, s92, 0x100000
	s_addc_u32 vcc_hi, s93, 0
	s_mov_b32 m0, s27
	s_nop 0
	global_load_lds_dwordx4 v134, s[92:93]
	s_add_i32 m0, s27, 0x2000
	s_nop 0
	global_load_lds_dwordx4 v138, s[92:93]
	s_add_i32 m0, s27, 0x4000
	s_nop 0
	global_load_lds_dwordx4 v134, vcc
	s_add_i32 m0, s27, 0x6000
	s_nop 0
	global_load_lds_dwordx4 v138, vcc
	s_sleep 2
	s_waitcnt lgkmcnt(0)
	s_waitcnt vmcnt(8)
	s_barrier
; #define PG8_STAGE(bufoff, gbase, voff) do { _Pragma("unroll") for (int _i = 0; _i < 2; ++_i) \
;         __builtin_amdgcn_global_load_lds((const unsigned*)((const char*)(gbase) + (voff)[_i]), (PG8_LAS unsigned*)(lds + (bufoff) + ldsw + _i * 8192), 16, 0, 0); } while (0)
; #define PG8_LDA(dst, b, h) do { _Pragma("unroll") for (int m = 0; m < 4; ++m) _Pragma("unroll") for (int k = 0; k < 2; ++k) dst[m][k] = *(const PG8_LAS bf16x8*)(lds + PG8_SA(b, h) + aoff + m * 2048 + k * 1024); } while (0)
; #define PG8_LDB(dst, b, h) do { _Pragma("unroll") for (int n = 0; n < 2; ++n) _Pragma("unroll") for (int k = 0; k < 2; ++k) dst[n][k] = *(const PG8_LAS bf16x8*)(lds + PG8_SB(b, h) + boff + n * 2048 + k * 1024); } while (0)
; #define PG8_MMA(ai, bj, At, Bt) do { __builtin_amdgcn_s_setprio(1); _Pragma("unroll") for (int m = 0; m < 4; ++m) _Pragma("unroll") for (int n = 0; n < 2; ++n) _Pragma("unroll") for (int k = 0; k < 2; ++k) \
;         acc[ai][bj][m][n] = __builtin_amdgcn_mfma_f32_16x16x32_bf16(Bt[n][k], At[m][k], acc[ai][bj][m][n], 0, 0, 0); __builtin_amdgcn_s_setprio(0); } while (0)
; #define PG8_WAIT_V(n) asm volatile("s_waitcnt vmcnt(" #n ")" ::: "memory")
; #define PG8_WAIT_L(n) asm volatile("s_waitcnt lgkmcnt(" #n ")" ::: "memory")
; #define PG8_BAR __builtin_amdgcn_s_barrier()
; #define PG8_SCHED __builtin_amdgcn_sched_barrier(0)
; template <class Epi, class Sched, bool ALIGN_EPI = false, bool SP2 = false>
; __device__ __forceinline__ void gemm_phase(PG8_LAS unsigned char* lds, const Gemm g, const Sched& S, const Epi& E) {
;     ...
;             PG8_LDB(B0, 1, 0); PG8_LDB(B1, 1, 1); PG8_SCHED; PG8_LDA(At, 1, 0); PG8_STAGE(PG8_SA(0, 1), a2 + hstep, voffA);
;             PG8_WAIT_V(8); PG8_WAIT_L(0); PG8_BAR; PG8_MMA(0, 0, At, B0); PG8_MMA(0, 1, At, B1); PG8_BAR; PG8_SCHED;
;             PG8_LDA(At, 1, 1); PG8_STAGE(PG8_SB(1, 0), b3, voffB); PG8_STAGE(PG8_SB(1, 1), b3 + hstep, voffB); PG8_STAGE(PG8_SA(1, 0), a3, voffA);
;             PG8_WAIT_V(8); PG8_WAIT_L(0); PG8_BAR; PG8_MMA(1, 0, At, B0); PG8_MMA(1, 1, At, B1); PG8_BAR; PG8_SCHED;
	s_setprio 2
	v_mfma_f32_16x16x32_bf16 v[38:41], v[150:153], v[190:193], v[38:41]
	v_mfma_f32_16x16x32_bf16 v[38:41], v[154:157], v[196:199], v[38:41]
	v_mfma_f32_16x16x32_bf16 v[30:33], v[158:161], v[190:193], v[30:33]
	v_mfma_f32_16x16x32_bf16 v[30:33], v[162:165], v[196:199], v[30:33]
	v_mfma_f32_16x16x32_bf16 v[50:53], v[174:177], v[190:193], v[50:53]
	v_mfma_f32_16x16x32_bf16 v[50:53], v[178:181], v[196:199], v[50:53]
	v_mfma_f32_16x16x32_bf16 v[46:49], v[182:185], v[190:193], v[46:49]
	v_mfma_f32_16x16x32_bf16 v[46:49], v[186:189], v[196:199], v[46:49]
	v_mfma_f32_16x16x32_bf16 v[118:121], v[182:185], v[200:203], v[118:121]
	v_mfma_f32_16x16x32_bf16 v[118:121], v[186:189], v[204:207], v[118:121]
	v_mfma_f32_16x16x32_bf16 v[122:125], v[174:177], v[200:203], v[122:125]
	v_mfma_f32_16x16x32_bf16 v[122:125], v[178:181], v[204:207], v[122:125]
	v_mfma_f32_16x16x32_bf16 v[126:129], v[158:161], v[200:203], v[126:129]
	v_mfma_f32_16x16x32_bf16 v[126:129], v[162:165], v[204:207], v[126:129]
	v_mfma_f32_16x16x32_bf16 v[130:133], v[150:153], v[200:203], v[130:133]
	v_mfma_f32_16x16x32_bf16 v[130:133], v[154:157], v[204:207], v[130:133]
	v_mfma_f32_16x16x32_bf16 v[114:117], v[150:153], v[208:211], v[114:117]
	v_mfma_f32_16x16x32_bf16 v[114:117], v[154:157], v[212:215], v[114:117]
	v_mfma_f32_16x16x32_bf16 v[110:113], v[158:161], v[208:211], v[110:113]
	v_mfma_f32_16x16x32_bf16 v[110:113], v[162:165], v[212:215], v[110:113]
	v_mfma_f32_16x16x32_bf16 v[106:109], v[174:177], v[208:211], v[106:109]
	v_mfma_f32_16x16x32_bf16 v[106:109], v[178:181], v[212:215], v[106:109]
	v_mfma_f32_16x16x32_bf16 v[102:105], v[182:185], v[208:211], v[102:105]
	v_mfma_f32_16x16x32_bf16 v[102:105], v[186:189], v[212:215], v[102:105]
	v_mfma_f32_16x16x32_bf16 v[86:89], v[182:185], v[220:223], v[86:89]
	v_mfma_f32_16x16x32_bf16 v[86:89], v[186:189], v[224:227], v[86:89]
	v_mfma_f32_16x16x32_bf16 v[90:93], v[174:177], v[220:223], v[90:93]
	v_mfma_f32_16x16x32_bf16 v[90:93], v[178:181], v[224:227], v[90:93]
	v_mfma_f32_16x16x32_bf16 v[94:97], v[158:161], v[220:223], v[94:97]
	v_mfma_f32_16x16x32_bf16 v[94:97], v[162:165], v[224:227], v[94:97]
	v_mfma_f32_16x16x32_bf16 v[98:101], v[150:153], v[220:223], v[98:101]
	v_mfma_f32_16x16x32_bf16 v[98:101], v[154:157], v[224:227], v[98:101]
	s_setprio 0
	ds_read_b128 v[190:193], v171 offset:49152
	ds_read_b128 v[196:199], v171 offset:50176
	ds_read_b128 v[200:203], v171 offset:51200
	ds_read_b128 v[204:207], v171 offset:52224
	ds_read_b128 v[208:211], v171 offset:53248
	ds_read_b128 v[212:215], v171 offset:54272
	ds_read_b128 v[220:223], v171 offset:55296
	ds_read_b128 v[224:227], v171 offset:56320
	s_add_u32 s0, s90, 0x80
	s_addc_u32 s1, s91, 0
	s_add_u32 vcc_lo, s0, 0x100000
	s_addc_u32 vcc_hi, s1, 0
	s_add_i32 m0, s27, 0x18000
	s_nop 0
	global_load_lds_dwordx4 v136, s[0:1]
	s_add_i32 m0, s27, 0x1a000
	s_nop 0
	global_load_lds_dwordx4 v140, s[0:1]
	s_add_i32 m0, s27, 0x1c000
	s_nop 0
	global_load_lds_dwordx4 v136, vcc
	s_add_i32 m0, s27, 0x1e000
	s_nop 0
	global_load_lds_dwordx4 v140, vcc
	s_sleep 2
	s_waitcnt lgkmcnt(0)
	s_waitcnt vmcnt(6)
	s_barrier
	s_setprio 2
	v_mfma_f32_16x16x32_bf16 v[70:73], v[182:185], v[190:193], v[70:73]
	v_mfma_f32_16x16x32_bf16 v[70:73], v[186:189], v[196:199], v[70:73]
	v_mfma_f32_16x16x32_bf16 v[74:77], v[174:177], v[190:193], v[74:77]
	v_mfma_f32_16x16x32_bf16 v[74:77], v[178:181], v[196:199], v[74:77]
	v_mfma_f32_16x16x32_bf16 v[78:81], v[158:161], v[190:193], v[78:81]
	v_mfma_f32_16x16x32_bf16 v[78:81], v[162:165], v[196:199], v[78:81]
	v_mfma_f32_16x16x32_bf16 v[82:85], v[150:153], v[190:193], v[82:85]
	v_mfma_f32_16x16x32_bf16 v[82:85], v[154:157], v[196:199], v[82:85]
	v_mfma_f32_16x16x32_bf16 v[66:69], v[150:153], v[200:203], v[66:69]
	v_mfma_f32_16x16x32_bf16 v[66:69], v[154:157], v[204:207], v[66:69]
	v_mfma_f32_16x16x32_bf16 v[62:65], v[158:161], v[200:203], v[62:65]
	v_mfma_f32_16x16x32_bf16 v[62:65], v[162:165], v[204:207], v[62:65]
	v_mfma_f32_16x16x32_bf16 v[58:61], v[174:177], v[200:203], v[58:61]
	v_mfma_f32_16x16x32_bf16 v[58:61], v[178:181], v[204:207], v[58:61]
	v_mfma_f32_16x16x32_bf16 v[54:57], v[182:185], v[200:203], v[54:57]
	v_mfma_f32_16x16x32_bf16 v[54:57], v[186:189], v[204:207], v[54:57]
	v_mfma_f32_16x16x32_bf16 v[22:25], v[182:185], v[208:211], v[22:25]
	v_mfma_f32_16x16x32_bf16 v[22:25], v[186:189], v[212:215], v[22:25]
	v_mfma_f32_16x16x32_bf16 v[26:29], v[174:177], v[208:211], v[26:29]
	v_mfma_f32_16x16x32_bf16 v[26:29], v[178:181], v[212:215], v[26:29]
	v_mfma_f32_16x16x32_bf16 v[34:37], v[158:161], v[208:211], v[34:37]
	v_mfma_f32_16x16x32_bf16 v[34:37], v[162:165], v[212:215], v[34:37]
	v_mfma_f32_16x16x32_bf16 v[42:45], v[150:153], v[208:211], v[42:45]
	v_mfma_f32_16x16x32_bf16 v[42:45], v[154:157], v[212:215], v[42:45]
	v_mfma_f32_16x16x32_bf16 v[18:21], v[150:153], v[220:223], v[18:21]
	v_mfma_f32_16x16x32_bf16 v[18:21], v[154:157], v[224:227], v[18:21]
	v_mfma_f32_16x16x32_bf16 v[14:17], v[158:161], v[220:223], v[14:17]
	v_mfma_f32_16x16x32_bf16 v[14:17], v[162:165], v[224:227], v[14:17]
	v_mfma_f32_16x16x32_bf16 v[8:11], v[174:177], v[220:223], v[10:13]
	v_mfma_f32_16x16x32_bf16 v[10:13], v[178:181], v[224:227], v[8:11]
	v_mfma_f32_16x16x32_bf16 v[4:7], v[182:185], v[220:223], v[4:7]
	v_mfma_f32_16x16x32_bf16 v[6:9], v[186:189], v[224:227], v[4:7]
	s_setprio 0
	s_add_i32 s23, s23, 2
	s_add_u32 s88, s88, 0x100
	s_addc_u32 s89, s89, 0
	s_add_u32 s9, s9, 0x100
	s_addc_u32 s21, s21, 0
	s_cmp_gt_u32 s23, 61
	s_cbranch_scc0 .Lip_h1

; #define PG8_STAGE(bufoff, gbase, voff) do { _Pragma("unroll") for (int _i = 0; _i < 2; ++_i) \
;         __builtin_amdgcn_global_load_lds((const unsigned*)((const char*)(gbase) + (voff)[_i]), (PG8_LAS unsigned*)(lds + (bufoff) + ldsw + _i * 8192), 16, 0, 0); } while (0)
; #define PG8_LDA(dst, b, h) do { _Pragma("unroll") for (int m = 0; m < 4; ++m) _Pragma("unroll") for (int k = 0; k < 2; ++k) dst[m][k] = *(const PG8_LAS bf16x8*)(lds + PG8_SA(b, h) + aoff + m * 2048 + k * 1024); } while (0)
; #define PG8_LDB(dst, b, h) do { _Pragma("unroll") for (int n = 0; n < 2; ++n) _Pragma("unroll") for (int k = 0; k < 2; ++k) dst[n][k] = *(const PG8_LAS bf16x8*)(lds + PG8_SB(b, h) + boff + n * 2048 + k * 1024); } while (0)
; #define PG8_MMA(ai, bj, At, Bt) do { __builtin_amdgcn_s_setprio(1); _Pragma("unroll") for (int m = 0; m < 4; ++m) _Pragma("unroll") for (int n = 0; n < 2; ++n) _Pragma("unroll") for (int k = 0; k < 2; ++k) \
;         acc[ai][bj][m][n] = __builtin_amdgcn_mfma_f32_16x16x32_bf16(Bt[n][k], At[m][k], acc[ai][bj][m][n], 0, 0, 0); __builtin_amdgcn_s_setprio(0); } while (0)
; #define PG8_WAIT_V(n) asm volatile("s_waitcnt vmcnt(" #n ")" ::: "memory")
; #define PG8_BAR __builtin_amdgcn_s_barrier()
; template <class Epi, class Sched, bool ALIGN_EPI = false, bool SP2 = false>
; __device__ __forceinline__ void gemm_phase(PG8_LAS unsigned char* lds, const Gemm g, const Sched& S, const Epi& E) {
;     ...
;         for (int t = 0; t < nt; t += 2) {
;             const bool last = (t == nt - 2);
;             const char* a1 = cA + (size_t)(t + 1) * kstep;
;             const char* a2 = last ? nA : cA + (size_t)(t + 2) * kstep; const char* b2 = last ? nB : cB + (size_t)(t + 2) * kstep;
;             const char* a3 = a2 + kstep; const char* b3 = b2 + kstep;
;             if (last && has_next) S.a_ready(nxt);
;             if constexpr (Epi::MIDK) { if (t == (nt >> 1)) { E.midk(acc, wr, fr); asm volatile("s_waitcnt lgkmcnt(0)" ::: "memory"); } }
;             if constexpr (SP2) {
;             PG8_LDB(B0, 0, 0); PG8_LDB(B1, 0, 1); PG8_SCHED; PG8_LDA(At, 0, 0); PG8_STAGE(PG8_SA(1, 1), a1 + hstep, voffA);
;             PG8_WAIT_V(8); PG8_WAIT_L(0); PG8_BAR; PG8_MMA(0, 0, At, B0); PG8_MMA(0, 1, At, B1); PG8_BAR; PG8_SCHED;
;             PG8_LDA(At, 0, 1); PG8_STAGE(PG8_SB(0, 0), b2, voffB); PG8_STAGE(PG8_SB(0, 1), b2 + hstep, voffB); PG8_STAGE(PG8_SA(0, 0), a2, voffA);
.LBB0_911:
	v_add_u32_e32 v3, s83, v219
	ds_read_b128 v[98:101], v3
	ds_read_b128 v[102:105], v3 offset:1024
	ds_read_b128 v[106:109], v3 offset:2048
	ds_read_b128 v[166:169], v3 offset:3072
	v_add_u32_e32 v3, s86, v219
	s_add_u32 s62, s58, s60
	ds_read_b128 v[170:173], v3
	ds_read_b128 v[174:177], v3 offset:1024
	ds_read_b128 v[178:181], v3 offset:2048
	ds_read_b128 v[182:185], v3 offset:3072
	s_addc_u32 s63, s59, s61
	s_add_u32 s62, s62, 0x100
	s_addc_u32 s63, s63, 0
	s_add_u32 s93, s90, s60
	s_addc_u32 s94, s91, s61
	s_cmpk_eq_i32 s60, 0x1f00
	s_cselect_b32 s65, s19, s63
	s_cselect_b32 s64, s21, s62
	s_cselect_b32 s63, s53, s94
	s_cselect_b32 s62, s57, s93
	v_lshl_add_u64 v[4:5], v[94:95], 0, s[60:61]
	s_add_i32 m0, s24, 0xc000
	ds_read_b128 v[186:189], v244
	ds_read_b128 v[190:193], v244 offset:1024
	ds_read_b128 v[196:199], v244 offset:2048
	ds_read_b128 v[200:203], v244 offset:3072
	ds_read_b128 v[204:207], v244 offset:4096
	ds_read_b128 v[208:211], v244 offset:5120
	ds_read_b128 v[212:215], v244 offset:6144
	ds_read_b128 v[246:249], v244 offset:7168
	global_load_lds_dwordx4 v[4:5], off
	v_lshl_add_u64 v[4:5], v[96:97], 0, s[60:61]
	s_add_i32 m0, s24, 0xe000
	s_nop 0
	global_load_lds_dwordx4 v[4:5], off
	s_waitcnt vmcnt(8)
	s_waitcnt lgkmcnt(0)
	s_barrier
	s_setprio 1
	s_waitcnt lgkmcnt(0)
	v_mfma_f32_16x16x32_bf16 v[146:149], v[98:101], v[186:189], v[146:149]
	v_mfma_f32_16x16x32_bf16 v[146:149], v[102:105], v[190:193], v[146:149]
	v_mfma_f32_16x16x32_bf16 v[142:145], v[106:109], v[186:189], v[142:145]
	v_mfma_f32_16x16x32_bf16 v[142:145], v[166:169], v[190:193], v[142:145]
	v_mfma_f32_16x16x32_bf16 v[66:69], v[170:173], v[186:189], v[66:69]
	v_mfma_f32_16x16x32_bf16 v[66:69], v[174:177], v[190:193], v[66:69]
	v_mfma_f32_16x16x32_bf16 v[62:65], v[178:181], v[186:189], v[62:65]
	v_mfma_f32_16x16x32_bf16 v[62:65], v[182:185], v[190:193], v[62:65]
	v_mfma_f32_16x16x32_bf16 v[54:57], v[178:181], v[196:199], v[54:57]
	v_mfma_f32_16x16x32_bf16 v[54:57], v[182:185], v[200:203], v[54:57]
	v_mfma_f32_16x16x32_bf16 v[58:61], v[170:173], v[196:199], v[58:61]
	v_mfma_f32_16x16x32_bf16 v[58:61], v[174:177], v[200:203], v[58:61]
	v_mfma_f32_16x16x32_bf16 v[134:137], v[106:109], v[196:199], v[134:137]
	v_mfma_f32_16x16x32_bf16 v[134:137], v[166:169], v[200:203], v[134:137]
	v_mfma_f32_16x16x32_bf16 v[138:141], v[98:101], v[196:199], v[138:141]
	v_mfma_f32_16x16x32_bf16 v[138:141], v[102:105], v[200:203], v[138:141]
	s_setprio 0
	s_setprio 1
	v_mfma_f32_16x16x32_bf16 v[130:133], v[98:101], v[204:207], v[130:133]
	v_mfma_f32_16x16x32_bf16 v[130:133], v[102:105], v[208:211], v[130:133]
	v_mfma_f32_16x16x32_bf16 v[126:129], v[106:109], v[204:207], v[126:129]
	v_mfma_f32_16x16x32_bf16 v[126:129], v[166:169], v[208:211], v[126:129]
	v_mfma_f32_16x16x32_bf16 v[50:53], v[170:173], v[204:207], v[50:53]
	v_mfma_f32_16x16x32_bf16 v[50:53], v[174:177], v[208:211], v[50:53]
	v_mfma_f32_16x16x32_bf16 v[46:49], v[178:181], v[204:207], v[46:49]
	v_mfma_f32_16x16x32_bf16 v[46:49], v[182:185], v[208:211], v[46:49]
	v_mfma_f32_16x16x32_bf16 v[38:41], v[178:181], v[212:215], v[38:41]
	v_mfma_f32_16x16x32_bf16 v[38:41], v[182:185], v[246:249], v[38:41]
	v_mfma_f32_16x16x32_bf16 v[42:45], v[170:173], v[212:215], v[42:45]
	v_mfma_f32_16x16x32_bf16 v[42:45], v[174:177], v[246:249], v[42:45]
	v_mfma_f32_16x16x32_bf16 v[118:121], v[106:109], v[212:215], v[118:121]
	v_mfma_f32_16x16x32_bf16 v[118:121], v[166:169], v[246:249], v[118:121]
	v_mfma_f32_16x16x32_bf16 v[122:125], v[98:101], v[212:215], v[122:125]
	v_mfma_f32_16x16x32_bf16 v[122:125], v[102:105], v[246:249], v[122:125]
	s_setprio 0
	s_barrier
	s_add_i32 s93, s83, s2
	v_lshl_add_u64 v[216:217], s[62:63], 0, v[152:153]
	s_mov_b32 m0, s93
	ds_read_b128 v[186:189], v244 offset:16384
	ds_read_b128 v[190:193], v244 offset:17408
	ds_read_b128 v[196:199], v244 offset:18432
	ds_read_b128 v[200:203], v244 offset:19456
	ds_read_b128 v[204:207], v244 offset:20480
	ds_read_b128 v[208:211], v244 offset:21504
	ds_read_b128 v[212:215], v244 offset:22528
	ds_read_b128 v[246:249], v244 offset:23552
	global_load_lds_dwordx4 v[216:217], off
	s_add_i32 m0, s93, 0x2000
	s_add_u32 s94, s62, 0x100000
	v_lshl_add_u64 v[250:251], s[62:63], 0, v[156:157]
	s_addc_u32 s95, s63, 0
	s_add_i32 s93, s86, s2
	global_load_lds_dwordx4 v[250:251], off
	v_lshl_add_u64 v[4:5], s[94:95], 0, v[152:153]
	s_mov_b32 m0, s93
	v_lshl_add_u64 v[252:253], s[64:65], 0, v[150:151]
	global_load_lds_dwordx4 v[4:5], off
	v_lshl_add_u64 v[4:5], s[94:95], 0, v[156:157]
	s_add_i32 m0, s93, 0x2000
	v_lshl_add_u64 v[222:223], s[64:65], 0, v[154:155]
	global_load_lds_dwordx4 v[4:5], off
	s_mov_b32 m0, s24
	s_nop 0
	global_load_lds_dwordx4 v[252:253], off
	s_mov_b32 m0, s25
	s_nop 0
	global_load_lds_dwordx4 v[222:223], off
	s_waitcnt vmcnt(8)
	s_waitcnt lgkmcnt(0)
	s_barrier
; #define PG8_STAGE(bufoff, gbase, voff) do { _Pragma("unroll") for (int _i = 0; _i < 2; ++_i) \
;         __builtin_amdgcn_global_load_lds((const unsigned*)((const char*)(gbase) + (voff)[_i]), (PG8_LAS unsigned*)(lds + (bufoff) + ldsw + _i * 8192), 16, 0, 0); } while (0)
; #define PG8_LDA(dst, b, h) do { _Pragma("unroll") for (int m = 0; m < 4; ++m) _Pragma("unroll") for (int k = 0; k < 2; ++k) dst[m][k] = *(const PG8_LAS bf16x8*)(lds + PG8_SA(b, h) + aoff + m * 2048 + k * 1024); } while (0)
; #define PG8_LDB(dst, b, h) do { _Pragma("unroll") for (int n = 0; n < 2; ++n) _Pragma("unroll") for (int k = 0; k < 2; ++k) dst[n][k] = *(const PG8_LAS bf16x8*)(lds + PG8_SB(b, h) + boff + n * 2048 + k * 1024); } while (0)
; #define PG8_MMA(ai, bj, At, Bt) do { __builtin_amdgcn_s_setprio(1); _Pragma("unroll") for (int m = 0; m < 4; ++m) _Pragma("unroll") for (int n = 0; n < 2; ++n) _Pragma("unroll") for (int k = 0; k < 2; ++k) \
;         acc[ai][bj][m][n] = __builtin_amdgcn_mfma_f32_16x16x32_bf16(Bt[n][k], At[m][k], acc[ai][bj][m][n], 0, 0, 0); __builtin_amdgcn_s_setprio(0); } while (0)
; #define PG8_WAIT_V(n) asm volatile("s_waitcnt vmcnt(" #n ")" ::: "memory")
; #define PG8_WAIT_L(n) asm volatile("s_waitcnt lgkmcnt(" #n ")" ::: "memory")
; #define PG8_BAR __builtin_amdgcn_s_barrier()
; #define PG8_SCHED __builtin_amdgcn_sched_barrier(0)
; template <class Epi, class Sched, bool ALIGN_EPI = false, bool SP2 = false>
; __device__ __forceinline__ void gemm_phase(PG8_LAS unsigned char* lds, const Gemm g, const Sched& S, const Epi& E) {
;     ...
;             PG8_LDA(At, 0, 1); PG8_STAGE(PG8_SB(0, 0), b2, voffB); PG8_STAGE(PG8_SB(0, 1), b2 + hstep, voffB); PG8_STAGE(PG8_SA(0, 0), a2, voffA);
;             PG8_WAIT_V(8); PG8_WAIT_L(0); PG8_BAR; PG8_MMA(1, 0, At, B0); PG8_MMA(1, 1, At, B1); PG8_BAR; PG8_SCHED;
;             PG8_LDB(B0, 1, 0); PG8_LDB(B1, 1, 1); PG8_SCHED; PG8_LDA(At, 1, 0); PG8_STAGE(PG8_SA(0, 1), a2 + hstep, voffA);
;             PG8_WAIT_V(8); PG8_WAIT_L(0); PG8_BAR; PG8_MMA(0, 0, At, B0); PG8_MMA(0, 1, At, B1); PG8_BAR; PG8_SCHED;
	s_setprio 1
	s_waitcnt lgkmcnt(0)
	v_mfma_f32_16x16x32_bf16 v[114:117], v[98:101], v[186:189], v[114:117]
	v_mfma_f32_16x16x32_bf16 v[114:117], v[102:105], v[190:193], v[114:117]
	v_mfma_f32_16x16x32_bf16 v[110:113], v[106:109], v[186:189], v[110:113]
	v_mfma_f32_16x16x32_bf16 v[110:113], v[166:169], v[190:193], v[110:113]
	v_mfma_f32_16x16x32_bf16 v[34:37], v[170:173], v[186:189], v[34:37]
	v_mfma_f32_16x16x32_bf16 v[34:37], v[174:177], v[190:193], v[34:37]
	v_mfma_f32_16x16x32_bf16 v[30:33], v[178:181], v[186:189], v[30:33]
	v_mfma_f32_16x16x32_bf16 v[30:33], v[182:185], v[190:193], v[30:33]
	v_mfma_f32_16x16x32_bf16 v[22:25], v[178:181], v[196:199], v[22:25]
	v_mfma_f32_16x16x32_bf16 v[22:25], v[182:185], v[200:203], v[22:25]
	v_mfma_f32_16x16x32_bf16 v[26:29], v[170:173], v[196:199], v[26:29]
	v_mfma_f32_16x16x32_bf16 v[26:29], v[174:177], v[200:203], v[26:29]
	v_mfma_f32_16x16x32_bf16 v[86:89], v[106:109], v[196:199], v[86:89]
	v_mfma_f32_16x16x32_bf16 v[86:89], v[166:169], v[200:203], v[86:89]
	v_mfma_f32_16x16x32_bf16 v[90:93], v[98:101], v[196:199], v[90:93]
	v_mfma_f32_16x16x32_bf16 v[90:93], v[102:105], v[200:203], v[90:93]
	s_setprio 0
	s_setprio 1
	v_mfma_f32_16x16x32_bf16 v[82:85], v[98:101], v[204:207], v[82:85]
	v_mfma_f32_16x16x32_bf16 v[82:85], v[102:105], v[208:211], v[82:85]
	v_mfma_f32_16x16x32_bf16 v[78:81], v[106:109], v[204:207], v[78:81]
	v_mfma_f32_16x16x32_bf16 v[78:81], v[166:169], v[208:211], v[78:81]
	v_mfma_f32_16x16x32_bf16 v[18:21], v[170:173], v[204:207], v[18:21]
	v_mfma_f32_16x16x32_bf16 v[18:21], v[174:177], v[208:211], v[18:21]
	v_mfma_f32_16x16x32_bf16 v[14:17], v[178:181], v[204:207], v[14:17]
	v_mfma_f32_16x16x32_bf16 v[14:17], v[182:185], v[208:211], v[14:17]
	v_mfma_f32_16x16x32_bf16 v[4:7], v[178:181], v[212:215], v[6:9]
	v_mfma_f32_16x16x32_bf16 v[4:7], v[182:185], v[246:249], v[4:7]
	v_mfma_f32_16x16x32_bf16 v[10:13], v[170:173], v[212:215], v[10:13]
	v_mfma_f32_16x16x32_bf16 v[10:13], v[174:177], v[246:249], v[10:13]
	v_mfma_f32_16x16x32_bf16 v[70:73], v[106:109], v[212:215], v[70:73]
	v_mfma_f32_16x16x32_bf16 v[70:73], v[166:169], v[246:249], v[70:73]
	v_mfma_f32_16x16x32_bf16 v[74:77], v[98:101], v[212:215], v[74:77]
	v_mfma_f32_16x16x32_bf16 v[74:77], v[102:105], v[246:249], v[74:77]
	s_setprio 0
	s_barrier
	s_add_i32 s93, 0, 0x18000
	v_add_u32_e32 v3, s93, v219
	s_add_i32 s94, 0, 0x1c000
	ds_read_b128 v[98:101], v3
	ds_read_b128 v[102:105], v3 offset:1024
	ds_read_b128 v[106:109], v3 offset:2048
	ds_read_b128 v[166:169], v3 offset:3072
	v_add_u32_e32 v3, s94, v219
	ds_read_b128 v[170:173], v3
	ds_read_b128 v[174:177], v3 offset:1024
	ds_read_b128 v[178:181], v3 offset:2048
	ds_read_b128 v[182:185], v3 offset:3072
	s_add_u32 s64, s64, 0x100000
	s_addc_u32 s65, s65, 0
	s_mov_b32 m0, s26
	v_lshl_add_u64 v[8:9], s[64:65], 0, v[150:151]
	ds_read_b128 v[186:189], v244 offset:32768
	ds_read_b128 v[190:193], v244 offset:33792
	ds_read_b128 v[196:199], v244 offset:34816
	ds_read_b128 v[200:203], v244 offset:35840
	ds_read_b128 v[204:207], v244 offset:36864
	ds_read_b128 v[208:211], v244 offset:37888
	ds_read_b128 v[212:215], v244 offset:38912
	ds_read_b128 v[246:249], v244 offset:39936
	global_load_lds_dwordx4 v[8:9], off
	v_lshl_add_u64 v[8:9], s[64:65], 0, v[154:155]
	s_mov_b32 m0, s27
	s_nop 0
	global_load_lds_dwordx4 v[8:9], off
	s_waitcnt vmcnt(8)
	s_waitcnt lgkmcnt(0)
	s_barrier
	s_setprio 1
	s_waitcnt lgkmcnt(0)
	v_mfma_f32_16x16x32_bf16 v[146:149], v[98:101], v[186:189], v[146:149]
	v_mfma_f32_16x16x32_bf16 v[146:149], v[102:105], v[190:193], v[146:149]
	v_mfma_f32_16x16x32_bf16 v[142:145], v[106:109], v[186:189], v[142:145]
	v_mfma_f32_16x16x32_bf16 v[142:145], v[166:169], v[190:193], v[142:145]
	v_mfma_f32_16x16x32_bf16 v[66:69], v[170:173], v[186:189], v[66:69]
	v_mfma_f32_16x16x32_bf16 v[66:69], v[174:177], v[190:193], v[66:69]
	v_mfma_f32_16x16x32_bf16 v[62:65], v[178:181], v[186:189], v[62:65]
	v_mfma_f32_16x16x32_bf16 v[62:65], v[182:185], v[190:193], v[62:65]
	v_mfma_f32_16x16x32_bf16 v[54:57], v[178:181], v[196:199], v[54:57]
	v_mfma_f32_16x16x32_bf16 v[54:57], v[182:185], v[200:203], v[54:57]
	v_mfma_f32_16x16x32_bf16 v[58:61], v[170:173], v[196:199], v[58:61]
	v_mfma_f32_16x16x32_bf16 v[58:61], v[174:177], v[200:203], v[58:61]
	v_mfma_f32_16x16x32_bf16 v[134:137], v[106:109], v[196:199], v[134:137]
	v_mfma_f32_16x16x32_bf16 v[134:137], v[166:169], v[200:203], v[134:137]
	v_mfma_f32_16x16x32_bf16 v[138:141], v[98:101], v[196:199], v[138:141]
	v_mfma_f32_16x16x32_bf16 v[138:141], v[102:105], v[200:203], v[138:141]
	s_setprio 0
	s_setprio 1
	v_mfma_f32_16x16x32_bf16 v[130:133], v[98:101], v[204:207], v[130:133]
	v_mfma_f32_16x16x32_bf16 v[130:133], v[102:105], v[208:211], v[130:133]
	v_mfma_f32_16x16x32_bf16 v[126:129], v[106:109], v[204:207], v[126:129]
	v_mfma_f32_16x16x32_bf16 v[126:129], v[166:169], v[208:211], v[126:129]
	v_mfma_f32_16x16x32_bf16 v[50:53], v[170:173], v[204:207], v[50:53]
	v_mfma_f32_16x16x32_bf16 v[50:53], v[174:177], v[208:211], v[50:53]
	v_mfma_f32_16x16x32_bf16 v[46:49], v[178:181], v[204:207], v[46:49]
	v_mfma_f32_16x16x32_bf16 v[46:49], v[182:185], v[208:211], v[46:49]
	v_mfma_f32_16x16x32_bf16 v[38:41], v[178:181], v[212:215], v[38:41]
	v_mfma_f32_16x16x32_bf16 v[38:41], v[182:185], v[246:249], v[38:41]
	v_mfma_f32_16x16x32_bf16 v[42:45], v[170:173], v[212:215], v[42:45]
	v_mfma_f32_16x16x32_bf16 v[42:45], v[174:177], v[246:249], v[42:45]
	v_mfma_f32_16x16x32_bf16 v[118:121], v[106:109], v[212:215], v[118:121]
	v_mfma_f32_16x16x32_bf16 v[118:121], v[166:169], v[246:249], v[118:121]
	v_mfma_f32_16x16x32_bf16 v[122:125], v[98:101], v[212:215], v[122:125]
	v_mfma_f32_16x16x32_bf16 v[122:125], v[102:105], v[246:249], v[122:125]
	s_setprio 0
	s_barrier
; #define PG8_STAGE(bufoff, gbase, voff) do { _Pragma("unroll") for (int _i = 0; _i < 2; ++_i) \
;         __builtin_amdgcn_global_load_lds((const unsigned*)((const char*)(gbase) + (voff)[_i]), (PG8_LAS unsigned*)(lds + (bufoff) + ldsw + _i * 8192), 16, 0, 0); } while (0)
; #define PG8_LDA(dst, b, h) do { _Pragma("unroll") for (int m = 0; m < 4; ++m) _Pragma("unroll") for (int k = 0; k < 2; ++k) dst[m][k] = *(const PG8_LAS bf16x8*)(lds + PG8_SA(b, h) + aoff + m * 2048 + k * 1024); } while (0)
; #define PG8_MMA(ai, bj, At, Bt) do { __builtin_amdgcn_s_setprio(1); _Pragma("unroll") for (int m = 0; m < 4; ++m) _Pragma("unroll") for (int n = 0; n < 2; ++n) _Pragma("unroll") for (int k = 0; k < 2; ++k) \
;         acc[ai][bj][m][n] = __builtin_amdgcn_mfma_f32_16x16x32_bf16(Bt[n][k], At[m][k], acc[ai][bj][m][n], 0, 0, 0); __builtin_amdgcn_s_setprio(0); } while (0)
; #define PG8_WAIT_V(n) asm volatile("s_waitcnt vmcnt(" #n ")" ::: "memory")
; #define PG8_WAIT_L(n) asm volatile("s_waitcnt lgkmcnt(" #n ")" ::: "memory")
; #define PG8_BAR __builtin_amdgcn_s_barrier()
; #define PG8_SCHED __builtin_amdgcn_sched_barrier(0)
; template <class Epi, class Sched, bool ALIGN_EPI = false, bool SP2 = false>
; __device__ __forceinline__ void gemm_phase(PG8_LAS unsigned char* lds, const Gemm g, const Sched& S, const Epi& E) {
;     ...
;             PG8_LDA(At, 1, 1); PG8_STAGE(PG8_SB(1, 0), b3, voffB); PG8_STAGE(PG8_SB(1, 1), b3 + hstep, voffB); PG8_STAGE(PG8_SA(1, 0), a3, voffA);
;             PG8_WAIT_V(8); PG8_WAIT_L(0); PG8_BAR; PG8_MMA(1, 0, At, B0); PG8_MMA(1, 1, At, B1); PG8_BAR; PG8_SCHED;
	s_add_i32 s64, s93, s2
	v_lshl_add_u64 v[8:9], v[216:217], 0, s[14:15]
	s_mov_b32 m0, s64
	ds_read_b128 v[186:189], v244 offset:49152
	ds_read_b128 v[190:193], v244 offset:50176
	ds_read_b128 v[196:199], v244 offset:51200
	ds_read_b128 v[200:203], v244 offset:52224
	ds_read_b128 v[204:207], v244 offset:53248
	ds_read_b128 v[208:211], v244 offset:54272
	ds_read_b128 v[212:215], v244 offset:55296
	ds_read_b128 v[246:249], v244 offset:56320
	global_load_lds_dwordx4 v[8:9], off
	s_add_i32 m0, s64, 0x2000
	s_add_u32 s62, s62, 0x100080
	v_lshl_add_u64 v[8:9], v[250:251], 0, s[14:15]
	s_addc_u32 s63, s63, 0
	s_add_i32 s64, s94, s2
	global_load_lds_dwordx4 v[8:9], off
	v_lshl_add_u64 v[8:9], s[62:63], 0, v[152:153]
	s_mov_b32 m0, s64
	s_nop 0
	global_load_lds_dwordx4 v[8:9], off
	v_lshl_add_u64 v[8:9], s[62:63], 0, v[156:157]
	s_add_i32 m0, s64, 0x2000
	s_nop 0
	global_load_lds_dwordx4 v[8:9], off
	v_lshl_add_u64 v[8:9], v[252:253], 0, s[14:15]
	s_mov_b32 m0, s66
	s_nop 0
	global_load_lds_dwordx4 v[8:9], off
	v_lshl_add_u64 v[8:9], v[222:223], 0, s[14:15]
	s_mov_b32 m0, s67
	s_nop 0
	global_load_lds_dwordx4 v[8:9], off
	s_waitcnt vmcnt(8)
	s_waitcnt lgkmcnt(0)
	s_barrier
	s_setprio 1
	s_waitcnt lgkmcnt(0)
	v_mfma_f32_16x16x32_bf16 v[30:33], v[178:181], v[186:189], v[30:33]
	v_mfma_f32_16x16x32_bf16 v[30:33], v[182:185], v[190:193], v[30:33]
	v_mfma_f32_16x16x32_bf16 v[34:37], v[170:173], v[186:189], v[34:37]
	v_mfma_f32_16x16x32_bf16 v[34:37], v[174:177], v[190:193], v[34:37]
	v_mfma_f32_16x16x32_bf16 v[110:113], v[106:109], v[186:189], v[110:113]
	v_mfma_f32_16x16x32_bf16 v[110:113], v[166:169], v[190:193], v[110:113]
	v_mfma_f32_16x16x32_bf16 v[114:117], v[98:101], v[186:189], v[114:117]
	v_mfma_f32_16x16x32_bf16 v[114:117], v[102:105], v[190:193], v[114:117]
	v_mfma_f32_16x16x32_bf16 v[90:93], v[98:101], v[196:199], v[90:93]
	v_mfma_f32_16x16x32_bf16 v[90:93], v[102:105], v[200:203], v[90:93]
	v_mfma_f32_16x16x32_bf16 v[86:89], v[106:109], v[196:199], v[86:89]
	v_mfma_f32_16x16x32_bf16 v[86:89], v[166:169], v[200:203], v[86:89]
	v_mfma_f32_16x16x32_bf16 v[26:29], v[170:173], v[196:199], v[26:29]
	v_mfma_f32_16x16x32_bf16 v[26:29], v[174:177], v[200:203], v[26:29]
	v_mfma_f32_16x16x32_bf16 v[22:25], v[178:181], v[196:199], v[22:25]
	v_mfma_f32_16x16x32_bf16 v[22:25], v[182:185], v[200:203], v[22:25]
	s_setprio 0
	s_setprio 1
	v_mfma_f32_16x16x32_bf16 v[14:17], v[178:181], v[204:207], v[14:17]
	v_mfma_f32_16x16x32_bf16 v[14:17], v[182:185], v[208:211], v[14:17]
	v_mfma_f32_16x16x32_bf16 v[18:21], v[170:173], v[204:207], v[18:21]
	v_mfma_f32_16x16x32_bf16 v[18:21], v[174:177], v[208:211], v[18:21]
	v_mfma_f32_16x16x32_bf16 v[78:81], v[106:109], v[204:207], v[78:81]
	v_mfma_f32_16x16x32_bf16 v[78:81], v[166:169], v[208:211], v[78:81]
	v_mfma_f32_16x16x32_bf16 v[82:85], v[98:101], v[204:207], v[82:85]
	v_mfma_f32_16x16x32_bf16 v[82:85], v[102:105], v[208:211], v[82:85]
	v_mfma_f32_16x16x32_bf16 v[74:77], v[98:101], v[212:215], v[74:77]
	v_mfma_f32_16x16x32_bf16 v[74:77], v[102:105], v[246:249], v[74:77]
	v_mfma_f32_16x16x32_bf16 v[70:73], v[106:109], v[212:215], v[70:73]
	v_mfma_f32_16x16x32_bf16 v[70:73], v[166:169], v[246:249], v[70:73]
	v_mfma_f32_16x16x32_bf16 v[8:11], v[170:173], v[212:215], v[10:13]
	v_mfma_f32_16x16x32_bf16 v[10:13], v[174:177], v[246:249], v[8:11]
	v_mfma_f32_16x16x32_bf16 v[4:7], v[178:181], v[212:215], v[4:7]
	v_mfma_f32_16x16x32_bf16 v[6:9], v[182:185], v[246:249], v[4:7]
	s_setprio 0
	s_barrier
	s_add_i32 s92, s92, 2
	s_add_u32 s60, s60, 0x100
	s_addc_u32 s61, s61, 0
	s_cmp_gt_u32 s92, 61
	s_cbranch_scc1 .LBB0_914
